# select passes: first MFMA of a stage issued ~25 VALU after the fragment reads (their LDS latency hides under the previous stage's head sums)
# baseline (speedup 1.0000x reference)
.Lp1_c1:
	ds_read_b128 v[176:179], v99 offset:8192
	ds_read_b128 v[180:183], v99 offset:12288
	ds_read_b128 v[230:233], v99 offset:9216
	ds_read_b128 v[234:237], v99 offset:13312
	ds_read_b128 v[238:241], v99 offset:10240
	ds_read_b128 v[242:245], v99 offset:14336
	ds_read_b128 v[246:249], v99 offset:11264
	ds_read_b128 v[50:53], v99 offset:15360
	v_max_i32_e32 v56, 0, v8
	v_max_i32_e32 v57, 0, v0
	v_max_i32_e32 v60, 0, v9
	v_max_i32_e32 v61, 0, v1
	v_max_i32_e32 v64, 0, v10
	v_max_i32_e32 v65, 0, v2
	v_max_i32_e32 v154, 0, v11
	v_max_i32_e32 v155, 0, v3
	v_mul_f32_e32 v156, v100, v56
	v_mul_f32_e32 v157, v101, v57
	v_fmac_f32_e32 v156, v102, v60
	v_fmac_f32_e32 v157, v103, v61
	v_fmac_f32_e32 v156, v104, v64
	v_fmac_f32_e32 v157, v105, v65
	v_fmac_f32_e32 v156, v106, v154
	v_fmac_f32_e32 v157, v107, v155
	v_max_i32_e32 v56, 0, v12
	v_max_i32_e32 v57, 0, v4
	v_max_i32_e32 v60, 0, v13
	v_max_i32_e32 v61, 0, v5
	v_max_i32_e32 v64, 0, v14
	v_max_i32_e32 v65, 0, v6
	v_max_i32_e32 v154, 0, v15
	v_max_i32_e32 v155, 0, v7
	s_waitcnt lgkmcnt(7)
	v_mfma_f32_32x32x16_bf16 v[198:213], v[34:37], v[176:179], 0
	v_fmac_f32_e32 v156, v108, v56
	v_fmac_f32_e32 v157, v109, v57
	v_fmac_f32_e32 v156, v110, v60
	v_fmac_f32_e32 v157, v111, v61
	v_fmac_f32_e32 v156, v112, v64
	v_fmac_f32_e32 v157, v113, v65
	v_fmac_f32_e32 v156, v114, v154
	v_fmac_f32_e32 v157, v115, v155
	v_bfe_u32 v56, v157, 19, 12
	s_waitcnt lgkmcnt(6)
	v_mfma_f32_32x32x16_bf16 v[214:229], v[34:37], v[180:183], 0
	s_waitcnt vmcnt(3)
	ds_write_b128 v140, v[20:23]
	s_add_i32 s1, s0, 5
	s_min_i32 s1, s1, s14
	v_mad_i64_i32 v[184:185], s[2:3], s1, v193, v[116:117]
	global_load_dwordx4 v[20:23], v[184:185], off
	v_bfe_u32 v64, v156, 19, 12
	v_med3_u32 v56, v56, s94, v194
	v_med3_u32 v64, v64, s94, v194
	v_sub_u32_e32 v57, 0x86f, v56
	v_add_u32_e32 v60, 0xfffffb90, v56
	v_sub_u32_e32 v65, 0x86f, v64
	v_add_u32_e32 v154, 0xfffffb90, v64
	v_cmp_gt_f32_e32 vcc, 0, v157
	s_nop 1
	s_waitcnt lgkmcnt(6)
	v_mfma_f32_32x32x16_bf16 v[198:213], v[38:41], v[230:233], v[198:213]
	v_cndmask_b32_e32 v56, v60, v57, vcc
	v_cmp_gt_f32_e32 vcc, 0, v156
	v_lshl_add_u32 v61, v56, 2, v33
	ds_add_u32 v61, v188
	v_cndmask_b32_e32 v64, v154, v65, vcc
	v_lshl_add_u32 v155, v64, 2, v33
	ds_add_u32 v155, v188 offset:4096
	v_max_i32_e32 v56, 0, v168
	v_max_i32_e32 v57, 0, v160
	s_waitcnt lgkmcnt(7)
	v_mfma_f32_32x32x16_bf16 v[214:229], v[38:41], v[234:237], v[214:229]
	v_max_i32_e32 v60, 0, v169
	v_max_i32_e32 v61, 0, v161
	v_max_i32_e32 v64, 0, v170
	v_max_i32_e32 v65, 0, v162
	v_max_i32_e32 v154, 0, v171
	v_max_i32_e32 v155, 0, v163
	v_mul_f32_e32 v156, v100, v56
	v_mul_f32_e32 v157, v101, v57
	v_fmac_f32_e32 v156, v102, v60
	s_waitcnt lgkmcnt(6)
	v_mfma_f32_32x32x16_bf16 v[198:213], v[42:45], v[238:241], v[198:213]
	v_fmac_f32_e32 v157, v103, v61
	v_fmac_f32_e32 v156, v104, v64
	v_fmac_f32_e32 v157, v105, v65
	v_fmac_f32_e32 v156, v106, v154
	v_fmac_f32_e32 v157, v107, v155
	v_max_i32_e32 v56, 0, v172
	v_max_i32_e32 v57, 0, v164
	v_max_i32_e32 v60, 0, v173
	v_max_i32_e32 v61, 0, v165
	s_waitcnt lgkmcnt(5)
	v_mfma_f32_32x32x16_bf16 v[214:229], v[42:45], v[242:245], v[214:229]
	v_max_i32_e32 v64, 0, v174
	v_max_i32_e32 v65, 0, v166
	v_max_i32_e32 v154, 0, v175
	v_max_i32_e32 v155, 0, v167
	v_fmac_f32_e32 v156, v108, v56
	v_fmac_f32_e32 v157, v109, v57
	v_fmac_f32_e32 v156, v110, v60
	v_fmac_f32_e32 v157, v111, v61
	v_fmac_f32_e32 v156, v112, v64
	s_waitcnt lgkmcnt(4)
	v_mfma_f32_32x32x16_bf16 v[198:213], v[46:49], v[246:249], v[198:213]
	v_fmac_f32_e32 v157, v113, v65
	v_fmac_f32_e32 v156, v114, v154
	v_fmac_f32_e32 v157, v115, v155
	v_bfe_u32 v56, v157, 19, 12
	v_bfe_u32 v64, v156, 19, 12
	v_med3_u32 v56, v56, s94, v194
	v_med3_u32 v64, v64, s94, v194
	v_sub_u32_e32 v57, 0x86f, v56
	v_add_u32_e32 v60, 0xfffffb90, v56
	s_waitcnt lgkmcnt(3)
	v_mfma_f32_32x32x16_bf16 v[214:229], v[46:49], v[50:53], v[214:229]
	v_sub_u32_e32 v65, 0x86f, v64
	v_add_u32_e32 v154, 0xfffffb90, v64
	v_cmp_gt_f32_e32 vcc, 0, v157
	s_nop 1
	v_cndmask_b32_e32 v56, v60, v57, vcc
	v_cmp_gt_f32_e32 vcc, 0, v156
	v_lshl_add_u32 v61, v56, 2, v33
	ds_add_u32 v61, v188
	v_cndmask_b32_e32 v64, v154, v65, vcc
	v_lshl_add_u32 v155, v64, 2, v33
	ds_add_u32 v155, v188 offset:4096
	s_waitcnt lgkmcnt(4)
	s_barrier
	s_add_u32 s0, s0, 1
	s_cmp_ge_u32 s0, s13
	s_cbranch_scc1 .Lp1_drain1
.Lp1_c2:
	ds_read_b128 v[176:179], v99 offset:0
	ds_read_b128 v[180:183], v99 offset:4096
	ds_read_b128 v[230:233], v99 offset:1024
	ds_read_b128 v[234:237], v99 offset:5120
	ds_read_b128 v[238:241], v99 offset:2048
	ds_read_b128 v[242:245], v99 offset:6144
	ds_read_b128 v[246:249], v99 offset:3072
	ds_read_b128 v[50:53], v99 offset:7168
	v_max_i32_e32 v56, 0, v206
	v_max_i32_e32 v57, 0, v198
	v_max_i32_e32 v60, 0, v207
	v_max_i32_e32 v61, 0, v199
	v_max_i32_e32 v64, 0, v208
	v_max_i32_e32 v65, 0, v200
	v_max_i32_e32 v154, 0, v209
	v_max_i32_e32 v155, 0, v201
	v_mul_f32_e32 v156, v100, v56
	v_mul_f32_e32 v157, v101, v57
	v_fmac_f32_e32 v156, v102, v60
	v_fmac_f32_e32 v157, v103, v61
	v_fmac_f32_e32 v156, v104, v64
	v_fmac_f32_e32 v157, v105, v65
	v_fmac_f32_e32 v156, v106, v154
	v_fmac_f32_e32 v157, v107, v155
	v_max_i32_e32 v56, 0, v210
	v_max_i32_e32 v57, 0, v202
	v_max_i32_e32 v60, 0, v211
	v_max_i32_e32 v61, 0, v203
	v_max_i32_e32 v64, 0, v212
	v_max_i32_e32 v65, 0, v204
	v_max_i32_e32 v154, 0, v213
	v_max_i32_e32 v155, 0, v205
	s_waitcnt lgkmcnt(7)
	v_mfma_f32_32x32x16_bf16 v[0:15], v[34:37], v[176:179], 0
	v_fmac_f32_e32 v156, v108, v56
	v_fmac_f32_e32 v157, v109, v57
	v_fmac_f32_e32 v156, v110, v60
	v_fmac_f32_e32 v157, v111, v61
	v_fmac_f32_e32 v156, v112, v64
	v_fmac_f32_e32 v157, v113, v65
	v_fmac_f32_e32 v156, v114, v154
	v_fmac_f32_e32 v157, v115, v155
	v_bfe_u32 v56, v157, 19, 12
	s_waitcnt lgkmcnt(6)
	v_mfma_f32_32x32x16_bf16 v[160:175], v[34:37], v[180:183], 0
	s_waitcnt vmcnt(3)
	ds_write_b128 v140, v[24:27] offset:8192
	s_add_i32 s1, s0, 5
	s_min_i32 s1, s1, s14
	v_mad_i64_i32 v[184:185], s[2:3], s1, v193, v[116:117]
	global_load_dwordx4 v[24:27], v[184:185], off
	v_bfe_u32 v64, v156, 19, 12
	v_med3_u32 v56, v56, s94, v194
	v_med3_u32 v64, v64, s94, v194
	v_sub_u32_e32 v57, 0x86f, v56
	v_add_u32_e32 v60, 0xfffffb90, v56
	v_sub_u32_e32 v65, 0x86f, v64
	v_add_u32_e32 v154, 0xfffffb90, v64
	v_cmp_gt_f32_e32 vcc, 0, v157
	s_nop 1
	s_waitcnt lgkmcnt(6)
	v_mfma_f32_32x32x16_bf16 v[0:15], v[38:41], v[230:233], v[0:15]
	v_cndmask_b32_e32 v56, v60, v57, vcc
	v_cmp_gt_f32_e32 vcc, 0, v156
	v_lshl_add_u32 v61, v56, 2, v33
	ds_add_u32 v61, v188
	v_cndmask_b32_e32 v64, v154, v65, vcc
	v_lshl_add_u32 v155, v64, 2, v33
	ds_add_u32 v155, v188 offset:4096
	v_max_i32_e32 v56, 0, v222
	v_max_i32_e32 v57, 0, v214
	s_waitcnt lgkmcnt(7)
	v_mfma_f32_32x32x16_bf16 v[160:175], v[38:41], v[234:237], v[160:175]
	v_max_i32_e32 v60, 0, v223
	v_max_i32_e32 v61, 0, v215
	v_max_i32_e32 v64, 0, v224
	v_max_i32_e32 v65, 0, v216
	v_max_i32_e32 v154, 0, v225
	v_max_i32_e32 v155, 0, v217
	v_mul_f32_e32 v156, v100, v56
	v_mul_f32_e32 v157, v101, v57
	v_fmac_f32_e32 v156, v102, v60
	s_waitcnt lgkmcnt(6)
	v_mfma_f32_32x32x16_bf16 v[0:15], v[42:45], v[238:241], v[0:15]
	v_fmac_f32_e32 v157, v103, v61
	v_fmac_f32_e32 v156, v104, v64
	v_fmac_f32_e32 v157, v105, v65
	v_fmac_f32_e32 v156, v106, v154
	v_fmac_f32_e32 v157, v107, v155
	v_max_i32_e32 v56, 0, v226
	v_max_i32_e32 v57, 0, v218
	v_max_i32_e32 v60, 0, v227
	v_max_i32_e32 v61, 0, v219
	s_waitcnt lgkmcnt(5)
	v_mfma_f32_32x32x16_bf16 v[160:175], v[42:45], v[242:245], v[160:175]
	v_max_i32_e32 v64, 0, v228
	v_max_i32_e32 v65, 0, v220
	v_max_i32_e32 v154, 0, v229
	v_max_i32_e32 v155, 0, v221
	v_fmac_f32_e32 v156, v108, v56
	v_fmac_f32_e32 v157, v109, v57
	v_fmac_f32_e32 v156, v110, v60
	v_fmac_f32_e32 v157, v111, v61
	v_fmac_f32_e32 v156, v112, v64
	s_waitcnt lgkmcnt(4)
	v_mfma_f32_32x32x16_bf16 v[0:15], v[46:49], v[246:249], v[0:15]
	v_fmac_f32_e32 v157, v113, v65
	v_fmac_f32_e32 v156, v114, v154
	v_fmac_f32_e32 v157, v115, v155
	v_bfe_u32 v56, v157, 19, 12
	v_bfe_u32 v64, v156, 19, 12
	v_med3_u32 v56, v56, s94, v194
	v_med3_u32 v64, v64, s94, v194
	v_sub_u32_e32 v57, 0x86f, v56
	v_add_u32_e32 v60, 0xfffffb90, v56
	s_waitcnt lgkmcnt(3)
	v_mfma_f32_32x32x16_bf16 v[160:175], v[46:49], v[50:53], v[160:175]
	v_sub_u32_e32 v65, 0x86f, v64
	v_add_u32_e32 v154, 0xfffffb90, v64
	v_cmp_gt_f32_e32 vcc, 0, v157
	s_nop 1
	v_cndmask_b32_e32 v56, v60, v57, vcc
	v_cmp_gt_f32_e32 vcc, 0, v156
	v_lshl_add_u32 v61, v56, 2, v33
	ds_add_u32 v61, v188
	v_cndmask_b32_e32 v64, v154, v65, vcc
	v_lshl_add_u32 v155, v64, 2, v33
	ds_add_u32 v155, v188 offset:4096
	s_waitcnt lgkmcnt(4)
	s_barrier
	s_add_u32 s0, s0, 1
	s_cmp_ge_u32 s0, s13
	s_cbranch_scc1 .Lp1_drain0
.Lp1_c3:
	ds_read_b128 v[176:179], v99 offset:8192
	ds_read_b128 v[180:183], v99 offset:12288
	ds_read_b128 v[230:233], v99 offset:9216
	ds_read_b128 v[234:237], v99 offset:13312
	ds_read_b128 v[238:241], v99 offset:10240
	ds_read_b128 v[242:245], v99 offset:14336
	ds_read_b128 v[246:249], v99 offset:11264
	ds_read_b128 v[50:53], v99 offset:15360
	v_max_i32_e32 v56, 0, v8
	v_max_i32_e32 v57, 0, v0
	v_max_i32_e32 v60, 0, v9
	v_max_i32_e32 v61, 0, v1
	v_max_i32_e32 v64, 0, v10
	v_max_i32_e32 v65, 0, v2
	v_max_i32_e32 v154, 0, v11
	v_max_i32_e32 v155, 0, v3
	v_mul_f32_e32 v156, v100, v56
	v_mul_f32_e32 v157, v101, v57
	v_fmac_f32_e32 v156, v102, v60
	v_fmac_f32_e32 v157, v103, v61
	v_fmac_f32_e32 v156, v104, v64
	v_fmac_f32_e32 v157, v105, v65
	v_fmac_f32_e32 v156, v106, v154
	v_fmac_f32_e32 v157, v107, v155
	v_max_i32_e32 v56, 0, v12
	v_max_i32_e32 v57, 0, v4
	v_max_i32_e32 v60, 0, v13
	v_max_i32_e32 v61, 0, v5
	v_max_i32_e32 v64, 0, v14
	v_max_i32_e32 v65, 0, v6
	v_max_i32_e32 v154, 0, v15
	v_max_i32_e32 v155, 0, v7
	s_waitcnt lgkmcnt(7)
	v_mfma_f32_32x32x16_bf16 v[198:213], v[34:37], v[176:179], 0
	v_fmac_f32_e32 v156, v108, v56
	v_fmac_f32_e32 v157, v109, v57
	v_fmac_f32_e32 v156, v110, v60
	v_fmac_f32_e32 v157, v111, v61
	v_fmac_f32_e32 v156, v112, v64
	v_fmac_f32_e32 v157, v113, v65
	v_fmac_f32_e32 v156, v114, v154
	v_fmac_f32_e32 v157, v115, v155
	v_bfe_u32 v56, v157, 19, 12
	s_waitcnt lgkmcnt(6)
	v_mfma_f32_32x32x16_bf16 v[214:229], v[34:37], v[180:183], 0
	s_waitcnt vmcnt(3)
	ds_write_b128 v140, v[28:31]
	s_add_i32 s1, s0, 5
	s_min_i32 s1, s1, s14
	v_mad_i64_i32 v[184:185], s[2:3], s1, v193, v[116:117]
	global_load_dwordx4 v[28:31], v[184:185], off
	v_bfe_u32 v64, v156, 19, 12
	v_med3_u32 v56, v56, s94, v194
	v_med3_u32 v64, v64, s94, v194
	v_sub_u32_e32 v57, 0x86f, v56
	v_add_u32_e32 v60, 0xfffffb90, v56
	v_sub_u32_e32 v65, 0x86f, v64
	v_add_u32_e32 v154, 0xfffffb90, v64
	v_cmp_gt_f32_e32 vcc, 0, v157
	s_nop 1
	s_waitcnt lgkmcnt(6)
	v_mfma_f32_32x32x16_bf16 v[198:213], v[38:41], v[230:233], v[198:213]
	v_cndmask_b32_e32 v56, v60, v57, vcc
	v_cmp_gt_f32_e32 vcc, 0, v156
	v_lshl_add_u32 v61, v56, 2, v33
	ds_add_u32 v61, v188
	v_cndmask_b32_e32 v64, v154, v65, vcc
	v_lshl_add_u32 v155, v64, 2, v33
	ds_add_u32 v155, v188 offset:4096
	v_max_i32_e32 v56, 0, v168
	v_max_i32_e32 v57, 0, v160
	s_waitcnt lgkmcnt(7)
	v_mfma_f32_32x32x16_bf16 v[214:229], v[38:41], v[234:237], v[214:229]
	v_max_i32_e32 v60, 0, v169
	v_max_i32_e32 v61, 0, v161
	v_max_i32_e32 v64, 0, v170
	v_max_i32_e32 v65, 0, v162
	v_max_i32_e32 v154, 0, v171
	v_max_i32_e32 v155, 0, v163
	v_mul_f32_e32 v156, v100, v56
	v_mul_f32_e32 v157, v101, v57
	v_fmac_f32_e32 v156, v102, v60
	s_waitcnt lgkmcnt(6)
	v_mfma_f32_32x32x16_bf16 v[198:213], v[42:45], v[238:241], v[198:213]
	v_fmac_f32_e32 v157, v103, v61
	v_fmac_f32_e32 v156, v104, v64
	v_fmac_f32_e32 v157, v105, v65
	v_fmac_f32_e32 v156, v106, v154
	v_fmac_f32_e32 v157, v107, v155
	v_max_i32_e32 v56, 0, v172
	v_max_i32_e32 v57, 0, v164
	v_max_i32_e32 v60, 0, v173
	v_max_i32_e32 v61, 0, v165
	s_waitcnt lgkmcnt(5)
	v_mfma_f32_32x32x16_bf16 v[214:229], v[42:45], v[242:245], v[214:229]
	v_max_i32_e32 v64, 0, v174
	v_max_i32_e32 v65, 0, v166
	v_max_i32_e32 v154, 0, v175
	v_max_i32_e32 v155, 0, v167
	v_fmac_f32_e32 v156, v108, v56
	v_fmac_f32_e32 v157, v109, v57
	v_fmac_f32_e32 v156, v110, v60
	v_fmac_f32_e32 v157, v111, v61
	v_fmac_f32_e32 v156, v112, v64
	s_waitcnt lgkmcnt(4)
	v_mfma_f32_32x32x16_bf16 v[198:213], v[46:49], v[246:249], v[198:213]
	v_fmac_f32_e32 v157, v113, v65
	v_fmac_f32_e32 v156, v114, v154
	v_fmac_f32_e32 v157, v115, v155
	v_bfe_u32 v56, v157, 19, 12
	v_bfe_u32 v64, v156, 19, 12
	v_med3_u32 v56, v56, s94, v194
	v_med3_u32 v64, v64, s94, v194
	v_sub_u32_e32 v57, 0x86f, v56
	v_add_u32_e32 v60, 0xfffffb90, v56
	s_waitcnt lgkmcnt(3)
	v_mfma_f32_32x32x16_bf16 v[214:229], v[46:49], v[50:53], v[214:229]
	v_sub_u32_e32 v65, 0x86f, v64
	v_add_u32_e32 v154, 0xfffffb90, v64
	v_cmp_gt_f32_e32 vcc, 0, v157
	s_nop 1
	v_cndmask_b32_e32 v56, v60, v57, vcc
	v_cmp_gt_f32_e32 vcc, 0, v156
	v_lshl_add_u32 v61, v56, 2, v33
	ds_add_u32 v61, v188
	v_cndmask_b32_e32 v64, v154, v65, vcc
	v_lshl_add_u32 v155, v64, 2, v33
	ds_add_u32 v155, v188 offset:4096
	s_waitcnt lgkmcnt(4)
	s_barrier
	s_add_u32 s0, s0, 1
	s_cmp_ge_u32 s0, s13
	s_cbranch_scc1 .Lp1_drain1
.Lp1_c0:
	ds_read_b128 v[176:179], v99 offset:0
	ds_read_b128 v[180:183], v99 offset:4096
	ds_read_b128 v[230:233], v99 offset:1024
	ds_read_b128 v[234:237], v99 offset:5120
	ds_read_b128 v[238:241], v99 offset:2048
	ds_read_b128 v[242:245], v99 offset:6144
	ds_read_b128 v[246:249], v99 offset:3072
	ds_read_b128 v[50:53], v99 offset:7168
	v_max_i32_e32 v56, 0, v206
	v_max_i32_e32 v57, 0, v198
	v_max_i32_e32 v60, 0, v207
	v_max_i32_e32 v61, 0, v199
	v_max_i32_e32 v64, 0, v208
	v_max_i32_e32 v65, 0, v200
	v_max_i32_e32 v154, 0, v209
	v_max_i32_e32 v155, 0, v201
	v_mul_f32_e32 v156, v100, v56
	v_mul_f32_e32 v157, v101, v57
	v_fmac_f32_e32 v156, v102, v60
	v_fmac_f32_e32 v157, v103, v61
	v_fmac_f32_e32 v156, v104, v64
	v_fmac_f32_e32 v157, v105, v65
	v_fmac_f32_e32 v156, v106, v154
	v_fmac_f32_e32 v157, v107, v155
	v_max_i32_e32 v56, 0, v210
	v_max_i32_e32 v57, 0, v202
	v_max_i32_e32 v60, 0, v211
	v_max_i32_e32 v61, 0, v203
	v_max_i32_e32 v64, 0, v212
	v_max_i32_e32 v65, 0, v204
	v_max_i32_e32 v154, 0, v213
	v_max_i32_e32 v155, 0, v205
	s_waitcnt lgkmcnt(7)
	v_mfma_f32_32x32x16_bf16 v[0:15], v[34:37], v[176:179], 0
	v_fmac_f32_e32 v156, v108, v56
	v_fmac_f32_e32 v157, v109, v57
	v_fmac_f32_e32 v156, v110, v60
	v_fmac_f32_e32 v157, v111, v61
	v_fmac_f32_e32 v156, v112, v64
	v_fmac_f32_e32 v157, v113, v65
	v_fmac_f32_e32 v156, v114, v154
	v_fmac_f32_e32 v157, v115, v155
	v_bfe_u32 v56, v157, 19, 12
	s_waitcnt lgkmcnt(6)
	v_mfma_f32_32x32x16_bf16 v[160:175], v[34:37], v[180:183], 0
	s_waitcnt vmcnt(3)
	ds_write_b128 v140, v[16:19] offset:8192
	s_add_i32 s1, s0, 5
	s_min_i32 s1, s1, s14
	v_mad_i64_i32 v[184:185], s[2:3], s1, v193, v[116:117]
	global_load_dwordx4 v[16:19], v[184:185], off
	v_bfe_u32 v64, v156, 19, 12
	v_med3_u32 v56, v56, s94, v194
	v_med3_u32 v64, v64, s94, v194
	v_sub_u32_e32 v57, 0x86f, v56
	v_add_u32_e32 v60, 0xfffffb90, v56
	v_sub_u32_e32 v65, 0x86f, v64
	v_add_u32_e32 v154, 0xfffffb90, v64
	v_cmp_gt_f32_e32 vcc, 0, v157
	s_nop 1
	s_waitcnt lgkmcnt(6)
	v_mfma_f32_32x32x16_bf16 v[0:15], v[38:41], v[230:233], v[0:15]
	v_cndmask_b32_e32 v56, v60, v57, vcc
	v_cmp_gt_f32_e32 vcc, 0, v156
	v_lshl_add_u32 v61, v56, 2, v33
	ds_add_u32 v61, v188
	v_cndmask_b32_e32 v64, v154, v65, vcc
	v_lshl_add_u32 v155, v64, 2, v33
	ds_add_u32 v155, v188 offset:4096
	v_max_i32_e32 v56, 0, v222
	v_max_i32_e32 v57, 0, v214
	s_waitcnt lgkmcnt(7)
	v_mfma_f32_32x32x16_bf16 v[160:175], v[38:41], v[234:237], v[160:175]
	v_max_i32_e32 v60, 0, v223
	v_max_i32_e32 v61, 0, v215
	v_max_i32_e32 v64, 0, v224
	v_max_i32_e32 v65, 0, v216
	v_max_i32_e32 v154, 0, v225
	v_max_i32_e32 v155, 0, v217
	v_mul_f32_e32 v156, v100, v56
	v_mul_f32_e32 v157, v101, v57
	v_fmac_f32_e32 v156, v102, v60
	s_waitcnt lgkmcnt(6)
	v_mfma_f32_32x32x16_bf16 v[0:15], v[42:45], v[238:241], v[0:15]
	v_fmac_f32_e32 v157, v103, v61
	v_fmac_f32_e32 v156, v104, v64
	v_fmac_f32_e32 v157, v105, v65
	v_fmac_f32_e32 v156, v106, v154
	v_fmac_f32_e32 v157, v107, v155
	v_max_i32_e32 v56, 0, v226
	v_max_i32_e32 v57, 0, v218
	v_max_i32_e32 v60, 0, v227
	v_max_i32_e32 v61, 0, v219
	s_waitcnt lgkmcnt(5)
	v_mfma_f32_32x32x16_bf16 v[160:175], v[42:45], v[242:245], v[160:175]
	v_max_i32_e32 v64, 0, v228
	v_max_i32_e32 v65, 0, v220
	v_max_i32_e32 v154, 0, v229
	v_max_i32_e32 v155, 0, v221
	v_fmac_f32_e32 v156, v108, v56
	v_fmac_f32_e32 v157, v109, v57
	v_fmac_f32_e32 v156, v110, v60
	v_fmac_f32_e32 v157, v111, v61
	v_fmac_f32_e32 v156, v112, v64
	s_waitcnt lgkmcnt(4)
	v_mfma_f32_32x32x16_bf16 v[0:15], v[46:49], v[246:249], v[0:15]
	v_fmac_f32_e32 v157, v113, v65
	v_fmac_f32_e32 v156, v114, v154
	v_fmac_f32_e32 v157, v115, v155
	v_bfe_u32 v56, v157, 19, 12
	v_bfe_u32 v64, v156, 19, 12
	v_med3_u32 v56, v56, s94, v194
	v_med3_u32 v64, v64, s94, v194
	v_sub_u32_e32 v57, 0x86f, v56
	v_add_u32_e32 v60, 0xfffffb90, v56
	s_waitcnt lgkmcnt(3)
	v_mfma_f32_32x32x16_bf16 v[160:175], v[46:49], v[50:53], v[160:175]
	v_sub_u32_e32 v65, 0x86f, v64
	v_add_u32_e32 v154, 0xfffffb90, v64
	v_cmp_gt_f32_e32 vcc, 0, v157
	s_nop 1
	v_cndmask_b32_e32 v56, v60, v57, vcc
	v_cmp_gt_f32_e32 vcc, 0, v156
	v_lshl_add_u32 v61, v56, 2, v33
	ds_add_u32 v61, v188
	v_cndmask_b32_e32 v64, v154, v65, vcc
	v_lshl_add_u32 v155, v64, 2, v33
	ds_add_u32 v155, v188 offset:4096
	s_waitcnt lgkmcnt(4)
	s_barrier
	s_add_u32 s0, s0, 1
	s_cmp_ge_u32 s0, s13
	s_cbranch_scc1 .Lp1_drain0
	s_branch .Lp1_c1

.Lp2_c1:
	ds_read_b128 v[164:167], v99 offset:8192
	ds_read_b128 v[168:171], v99 offset:12288
	ds_read_b128 v[172:175], v99 offset:9216
	ds_read_b128 v[176:179], v99 offset:13312
	ds_read_b128 v[230:233], v99 offset:10240
	ds_read_b128 v[234:237], v99 offset:14336
	ds_read_b128 v[238:241], v99 offset:11264
	ds_read_b128 v[242:245], v99 offset:15360
	v_max_i32_e32 v246, 0, v24
	v_max_i32_e32 v247, 0, v16
	v_max_i32_e32 v248, 0, v25
	v_max_i32_e32 v249, 0, v17
	v_fma_f32 v184, v100, v246, 0
	v_fma_f32 v185, v101, v247, 0
	v_fmac_f32_e32 v184, v102, v248
	v_fmac_f32_e32 v185, v103, v249
	v_max_i32_e32 v246, 0, v26
	v_max_i32_e32 v247, 0, v18
	v_max_i32_e32 v248, 0, v27
	v_max_i32_e32 v249, 0, v19
	v_fmac_f32_e32 v184, v104, v246
	v_fmac_f32_e32 v185, v105, v247
	v_fmac_f32_e32 v184, v106, v248
	v_fmac_f32_e32 v185, v107, v249
	v_max_i32_e32 v246, 0, v28
	v_max_i32_e32 v247, 0, v20
	v_max_i32_e32 v248, 0, v29
	v_max_i32_e32 v249, 0, v21
	s_waitcnt lgkmcnt(7)
	v_mfma_f32_32x32x16_bf16 v[198:213], v[34:37], v[164:167], 0
	v_fmac_f32_e32 v184, v108, v246
	v_fmac_f32_e32 v185, v109, v247
	v_fmac_f32_e32 v184, v110, v248
	v_fmac_f32_e32 v185, v111, v249
	v_max_i32_e32 v246, 0, v30
	v_max_i32_e32 v247, 0, v22
	v_max_i32_e32 v248, 0, v31
	v_max_i32_e32 v249, 0, v23
	s_waitcnt lgkmcnt(6)
	v_mfma_f32_32x32x16_bf16 v[214:229], v[34:37], v[168:171], 0
	s_waitcnt vmcnt(3)
	ds_write_b128 v140, v[54:57]
	s_add_i32 s4, s18, 5
	s_min_i32 s4, s4, s14
	v_mad_i64_i32 v[164:165], s[4:5], s4, v193, v[116:117]
	global_load_dwordx4 v[54:57], v[164:165], off
	v_fmac_f32_e32 v184, v112, v246
	v_fmac_f32_e32 v185, v113, v247
	v_fmac_f32_e32 v184, v114, v248
	v_fmac_f32_e32 v185, v115, v249
	v_cmp_le_f32_e64 s[52:53], v250, v185
	v_cmp_le_f32_e32 vcc, v156, v185
	s_andn2_b64 vcc, vcc, s[52:53]
	v_writelane_b32 v33, s52, 0
	v_writelane_b32 v33, s53, 4
	s_cbranch_vccz .Lp2_skip1
	v_mov_b32_e32 v246, vcc_hi
	v_mov_b32_e32 v247, vcc_lo
	v_cndmask_b32_e64 v246, v246, v247, s[48:49]
	s_and_saveexec_b64 s[4:5], vcc
	v_and_b32_e32 v247, v246, v127
	v_bcnt_u32_b32 v247, v247, v119
	v_cmp_gt_u32_e32 vcc, s35, v247
	v_ashrrev_i32_e32 v248, 31, v185
	v_add_u32_e32 v154, s0, v78
	v_bitop3_b32 v155, v185, v248, s97 bitop3:0x1e
	v_lshl_add_u32 v248, v247, 3, v160
	s_and_b64 exec, exec, vcc
	ds_write_b64 v248, v[154:155] offset:2048
	s_mov_b64 exec, s[4:5]
	v_bcnt_u32_b32 v119, v246, v119
.Lp2_skip1:
	s_waitcnt lgkmcnt(6)
	v_mfma_f32_32x32x16_bf16 v[198:213], v[38:41], v[172:175], v[198:213]
	v_cmp_le_f32_e64 s[52:53], v197, v184
	v_cmp_le_f32_e32 vcc, v157, v184
	s_andn2_b64 vcc, vcc, s[52:53]
	v_writelane_b32 v33, s52, 2
	v_writelane_b32 v33, s53, 6
	s_cbranch_vccz .Lp2_skip2
	v_mov_b32_e32 v246, vcc_hi
	v_mov_b32_e32 v247, vcc_lo
	v_cndmask_b32_e64 v246, v246, v247, s[48:49]
	s_and_saveexec_b64 s[4:5], vcc
	v_and_b32_e32 v247, v246, v127
	v_bcnt_u32_b32 v247, v247, v118
	v_cmp_gt_u32_e32 vcc, s35, v247
	v_ashrrev_i32_e32 v248, 31, v184
	v_add_u32_e32 v154, s0, v78
	v_bitop3_b32 v155, v184, v248, s97 bitop3:0x1e
	v_lshl_add_u32 v248, v247, 3, v161
	s_and_b64 exec, exec, vcc
	ds_write_b64 v248, v[154:155] offset:2048
	s_mov_b64 exec, s[4:5]
	v_bcnt_u32_b32 v118, v246, v118
.Lp2_skip2:
	s_waitcnt lgkmcnt(5)
	v_mfma_f32_32x32x16_bf16 v[214:229], v[38:41], v[176:179], v[214:229]
	v_max_i32_e32 v246, 0, v8
	v_max_i32_e32 v247, 0, v0
	v_max_i32_e32 v248, 0, v9
	v_max_i32_e32 v249, 0, v1
	v_fma_f32 v184, v100, v246, 0
	v_fma_f32 v185, v101, v247, 0
	s_waitcnt lgkmcnt(4)
	v_mfma_f32_32x32x16_bf16 v[198:213], v[42:45], v[230:233], v[198:213]
	v_fmac_f32_e32 v184, v102, v248
	v_fmac_f32_e32 v185, v103, v249
	v_max_i32_e32 v246, 0, v10
	v_max_i32_e32 v247, 0, v2
	v_max_i32_e32 v248, 0, v11
	v_max_i32_e32 v249, 0, v3
	v_fmac_f32_e32 v184, v104, v246
	v_fmac_f32_e32 v185, v105, v247
	s_waitcnt lgkmcnt(3)
	v_mfma_f32_32x32x16_bf16 v[214:229], v[42:45], v[234:237], v[214:229]
	v_fmac_f32_e32 v184, v106, v248
	v_fmac_f32_e32 v185, v107, v249
	v_max_i32_e32 v246, 0, v12
	v_max_i32_e32 v247, 0, v4
	v_max_i32_e32 v248, 0, v13
	v_max_i32_e32 v249, 0, v5
	v_fmac_f32_e32 v184, v108, v246
	v_fmac_f32_e32 v185, v109, v247
	s_waitcnt lgkmcnt(2)
	v_mfma_f32_32x32x16_bf16 v[198:213], v[46:49], v[238:241], v[198:213]
	v_fmac_f32_e32 v184, v110, v248
	v_fmac_f32_e32 v185, v111, v249
	v_max_i32_e32 v246, 0, v14
	v_max_i32_e32 v247, 0, v6
	v_max_i32_e32 v248, 0, v15
	v_max_i32_e32 v249, 0, v7
	v_fmac_f32_e32 v184, v112, v246
	v_fmac_f32_e32 v185, v113, v247
	s_waitcnt lgkmcnt(1)
	v_mfma_f32_32x32x16_bf16 v[214:229], v[46:49], v[242:245], v[214:229]
	v_fmac_f32_e32 v184, v114, v248
	v_fmac_f32_e32 v185, v115, v249
	v_cmp_le_f32_e64 s[52:53], v250, v185
	v_cmp_le_f32_e32 vcc, v156, v185
	s_andn2_b64 vcc, vcc, s[52:53]
	v_writelane_b32 v33, s52, 1
	v_writelane_b32 v33, s53, 5
	s_cbranch_vccz .Lp2_skip3
	v_mov_b32_e32 v246, vcc_hi
	v_mov_b32_e32 v247, vcc_lo
	v_cndmask_b32_e64 v246, v246, v247, s[48:49]
	s_and_saveexec_b64 s[4:5], vcc
	v_and_b32_e32 v247, v246, v127
	v_bcnt_u32_b32 v247, v247, v119
	v_cmp_gt_u32_e32 vcc, s35, v247
	v_ashrrev_i32_e32 v248, 31, v185
	v_add_u32_e32 v154, s0, v96
	v_bitop3_b32 v155, v185, v248, s97 bitop3:0x1e
	v_lshl_add_u32 v248, v247, 3, v160
	s_and_b64 exec, exec, vcc
	ds_write_b64 v248, v[154:155] offset:2048
	s_mov_b64 exec, s[4:5]
	v_bcnt_u32_b32 v119, v246, v119

.Lp2_c2:
	ds_read_b128 v[164:167], v99 offset:0
	ds_read_b128 v[168:171], v99 offset:4096
	ds_read_b128 v[172:175], v99 offset:1024
	ds_read_b128 v[176:179], v99 offset:5120
	ds_read_b128 v[230:233], v99 offset:2048
	ds_read_b128 v[234:237], v99 offset:6144
	ds_read_b128 v[238:241], v99 offset:3072
	ds_read_b128 v[242:245], v99 offset:7168
	v_max_i32_e32 v246, 0, v206
	v_max_i32_e32 v247, 0, v198
	v_max_i32_e32 v248, 0, v207
	v_max_i32_e32 v249, 0, v199
	v_fma_f32 v184, v100, v246, 0
	v_fma_f32 v185, v101, v247, 0
	v_fmac_f32_e32 v184, v102, v248
	v_fmac_f32_e32 v185, v103, v249
	v_max_i32_e32 v246, 0, v208
	v_max_i32_e32 v247, 0, v200
	v_max_i32_e32 v248, 0, v209
	v_max_i32_e32 v249, 0, v201
	v_fmac_f32_e32 v184, v104, v246
	v_fmac_f32_e32 v185, v105, v247
	v_fmac_f32_e32 v184, v106, v248
	v_fmac_f32_e32 v185, v107, v249
	v_max_i32_e32 v246, 0, v210
	v_max_i32_e32 v247, 0, v202
	v_max_i32_e32 v248, 0, v211
	v_max_i32_e32 v249, 0, v203
	s_waitcnt lgkmcnt(7)
	v_mfma_f32_32x32x16_bf16 v[16:31], v[34:37], v[164:167], 0
	v_fmac_f32_e32 v184, v108, v246
	v_fmac_f32_e32 v185, v109, v247
	v_fmac_f32_e32 v184, v110, v248
	v_fmac_f32_e32 v185, v111, v249
	v_max_i32_e32 v246, 0, v212
	v_max_i32_e32 v247, 0, v204
	v_max_i32_e32 v248, 0, v213
	v_max_i32_e32 v249, 0, v205
	s_waitcnt lgkmcnt(6)
	v_mfma_f32_32x32x16_bf16 v[0:15], v[34:37], v[168:171], 0
	s_waitcnt vmcnt(3)
	ds_write_b128 v140, v[58:61] offset:8192
	s_add_i32 s4, s18, 5
	s_min_i32 s4, s4, s14
	v_mad_i64_i32 v[164:165], s[4:5], s4, v193, v[116:117]
	global_load_dwordx4 v[58:61], v[164:165], off
	v_fmac_f32_e32 v184, v112, v246
	v_fmac_f32_e32 v185, v113, v247
	v_fmac_f32_e32 v184, v114, v248
	v_fmac_f32_e32 v185, v115, v249
	v_cmp_le_f32_e64 s[52:53], v250, v185
	v_cmp_le_f32_e32 vcc, v156, v185
	s_andn2_b64 vcc, vcc, s[52:53]
	v_writelane_b32 v33, s52, 0
	v_writelane_b32 v33, s53, 4
	s_cbranch_vccz .Lp2_skip5
	v_mov_b32_e32 v246, vcc_hi
	v_mov_b32_e32 v247, vcc_lo
	v_cndmask_b32_e64 v246, v246, v247, s[48:49]
	s_and_saveexec_b64 s[4:5], vcc
	v_and_b32_e32 v247, v246, v127
	v_bcnt_u32_b32 v247, v247, v119
	v_cmp_gt_u32_e32 vcc, s35, v247
	v_ashrrev_i32_e32 v248, 31, v185
	v_add_u32_e32 v154, s0, v92
	v_bitop3_b32 v155, v185, v248, s97 bitop3:0x1e
	v_lshl_add_u32 v248, v247, 3, v160
	s_and_b64 exec, exec, vcc
	ds_write_b64 v248, v[154:155] offset:2048
	s_mov_b64 exec, s[4:5]
	v_bcnt_u32_b32 v119, v246, v119
.Lp2_skip5:
	s_waitcnt lgkmcnt(6)
	v_mfma_f32_32x32x16_bf16 v[16:31], v[38:41], v[172:175], v[16:31]
	v_cmp_le_f32_e64 s[52:53], v197, v184
	v_cmp_le_f32_e32 vcc, v157, v184
	s_andn2_b64 vcc, vcc, s[52:53]
	v_writelane_b32 v33, s52, 2
	v_writelane_b32 v33, s53, 6
	s_cbranch_vccz .Lp2_skip6
	v_mov_b32_e32 v246, vcc_hi
	v_mov_b32_e32 v247, vcc_lo
	v_cndmask_b32_e64 v246, v246, v247, s[48:49]
	s_and_saveexec_b64 s[4:5], vcc
	v_and_b32_e32 v247, v246, v127
	v_bcnt_u32_b32 v247, v247, v118
	v_cmp_gt_u32_e32 vcc, s35, v247
	v_ashrrev_i32_e32 v248, 31, v184
	v_add_u32_e32 v154, s0, v92
	v_bitop3_b32 v155, v184, v248, s97 bitop3:0x1e
	v_lshl_add_u32 v248, v247, 3, v161
	s_and_b64 exec, exec, vcc
	ds_write_b64 v248, v[154:155] offset:2048
	s_mov_b64 exec, s[4:5]
	v_bcnt_u32_b32 v118, v246, v118
.Lp2_skip6:
	s_waitcnt lgkmcnt(5)
	v_mfma_f32_32x32x16_bf16 v[0:15], v[38:41], v[176:179], v[0:15]
	v_max_i32_e32 v246, 0, v222
	v_max_i32_e32 v247, 0, v214
	v_max_i32_e32 v248, 0, v223
	v_max_i32_e32 v249, 0, v215
	v_fma_f32 v184, v100, v246, 0
	v_fma_f32 v185, v101, v247, 0
	s_waitcnt lgkmcnt(4)
	v_mfma_f32_32x32x16_bf16 v[16:31], v[42:45], v[230:233], v[16:31]
	v_fmac_f32_e32 v184, v102, v248
	v_fmac_f32_e32 v185, v103, v249
	v_max_i32_e32 v246, 0, v224
	v_max_i32_e32 v247, 0, v216
	v_max_i32_e32 v248, 0, v225
	v_max_i32_e32 v249, 0, v217
	v_fmac_f32_e32 v184, v104, v246
	v_fmac_f32_e32 v185, v105, v247
	s_waitcnt lgkmcnt(3)
	v_mfma_f32_32x32x16_bf16 v[0:15], v[42:45], v[234:237], v[0:15]
	v_fmac_f32_e32 v184, v106, v248
	v_fmac_f32_e32 v185, v107, v249
	v_max_i32_e32 v246, 0, v226
	v_max_i32_e32 v247, 0, v218
	v_max_i32_e32 v248, 0, v227
	v_max_i32_e32 v249, 0, v219
	v_fmac_f32_e32 v184, v108, v246
	v_fmac_f32_e32 v185, v109, v247
	s_waitcnt lgkmcnt(2)
	v_mfma_f32_32x32x16_bf16 v[16:31], v[46:49], v[238:241], v[16:31]
	v_fmac_f32_e32 v184, v110, v248
	v_fmac_f32_e32 v185, v111, v249
	v_max_i32_e32 v246, 0, v228
	v_max_i32_e32 v247, 0, v220
	v_max_i32_e32 v248, 0, v229
	v_max_i32_e32 v249, 0, v221
	v_fmac_f32_e32 v184, v112, v246
	v_fmac_f32_e32 v185, v113, v247
	s_waitcnt lgkmcnt(1)
	v_mfma_f32_32x32x16_bf16 v[0:15], v[46:49], v[242:245], v[0:15]
	v_fmac_f32_e32 v184, v114, v248
	v_fmac_f32_e32 v185, v115, v249
	v_cmp_le_f32_e64 s[52:53], v250, v185
	v_cmp_le_f32_e32 vcc, v156, v185
	s_andn2_b64 vcc, vcc, s[52:53]
	v_writelane_b32 v33, s52, 1
	v_writelane_b32 v33, s53, 5
	s_cbranch_vccz .Lp2_skip7
	v_mov_b32_e32 v246, vcc_hi
	v_mov_b32_e32 v247, vcc_lo
	v_cndmask_b32_e64 v246, v246, v247, s[48:49]
	s_and_saveexec_b64 s[4:5], vcc
	v_and_b32_e32 v247, v246, v127
	v_bcnt_u32_b32 v247, v247, v119
	v_cmp_gt_u32_e32 vcc, s35, v247
	v_ashrrev_i32_e32 v248, 31, v185
	v_add_u32_e32 v154, s0, v94
	v_bitop3_b32 v155, v185, v248, s97 bitop3:0x1e
	v_lshl_add_u32 v248, v247, 3, v160
	s_and_b64 exec, exec, vcc
	ds_write_b64 v248, v[154:155] offset:2048
	s_mov_b64 exec, s[4:5]
	v_bcnt_u32_b32 v119, v246, v119

.Lp2_c3:
	ds_read_b128 v[164:167], v99 offset:8192
	ds_read_b128 v[168:171], v99 offset:12288
	ds_read_b128 v[172:175], v99 offset:9216
	ds_read_b128 v[176:179], v99 offset:13312
	ds_read_b128 v[230:233], v99 offset:10240
	ds_read_b128 v[234:237], v99 offset:14336
	ds_read_b128 v[238:241], v99 offset:11264
	ds_read_b128 v[242:245], v99 offset:15360
	v_max_i32_e32 v246, 0, v24
	v_max_i32_e32 v247, 0, v16
	v_max_i32_e32 v248, 0, v25
	v_max_i32_e32 v249, 0, v17
	v_fma_f32 v184, v100, v246, 0
	v_fma_f32 v185, v101, v247, 0
	v_fmac_f32_e32 v184, v102, v248
	v_fmac_f32_e32 v185, v103, v249
	v_max_i32_e32 v246, 0, v26
	v_max_i32_e32 v247, 0, v18
	v_max_i32_e32 v248, 0, v27
	v_max_i32_e32 v249, 0, v19
	v_fmac_f32_e32 v184, v104, v246
	v_fmac_f32_e32 v185, v105, v247
	v_fmac_f32_e32 v184, v106, v248
	v_fmac_f32_e32 v185, v107, v249
	v_max_i32_e32 v246, 0, v28
	v_max_i32_e32 v247, 0, v20
	v_max_i32_e32 v248, 0, v29
	v_max_i32_e32 v249, 0, v21
	s_waitcnt lgkmcnt(7)
	v_mfma_f32_32x32x16_bf16 v[198:213], v[34:37], v[164:167], 0
	v_fmac_f32_e32 v184, v108, v246
	v_fmac_f32_e32 v185, v109, v247
	v_fmac_f32_e32 v184, v110, v248
	v_fmac_f32_e32 v185, v111, v249
	v_max_i32_e32 v246, 0, v30
	v_max_i32_e32 v247, 0, v22
	v_max_i32_e32 v248, 0, v31
	v_max_i32_e32 v249, 0, v23
	s_waitcnt lgkmcnt(6)
	v_mfma_f32_32x32x16_bf16 v[214:229], v[34:37], v[168:171], 0
	s_waitcnt vmcnt(3)
	ds_write_b128 v140, v[62:65]
	s_add_i32 s4, s18, 5
	s_min_i32 s4, s4, s14
	v_mad_i64_i32 v[164:165], s[4:5], s4, v193, v[116:117]
	global_load_dwordx4 v[62:65], v[164:165], off
	v_fmac_f32_e32 v184, v112, v246
	v_fmac_f32_e32 v185, v113, v247
	v_fmac_f32_e32 v184, v114, v248
	v_fmac_f32_e32 v185, v115, v249
	v_cmp_le_f32_e64 s[52:53], v250, v185
	v_cmp_le_f32_e32 vcc, v156, v185
	s_andn2_b64 vcc, vcc, s[52:53]
	v_writelane_b32 v33, s52, 0
	v_writelane_b32 v33, s53, 4
	s_cbranch_vccz .Lp2_skip9
	v_mov_b32_e32 v246, vcc_hi
	v_mov_b32_e32 v247, vcc_lo
	v_cndmask_b32_e64 v246, v246, v247, s[48:49]
	s_and_saveexec_b64 s[4:5], vcc
	v_and_b32_e32 v247, v246, v127
	v_bcnt_u32_b32 v247, v247, v119
	v_cmp_gt_u32_e32 vcc, s35, v247
	v_ashrrev_i32_e32 v248, 31, v185
	v_add_u32_e32 v154, s0, v90
	v_bitop3_b32 v155, v185, v248, s97 bitop3:0x1e
	v_lshl_add_u32 v248, v247, 3, v160
	s_and_b64 exec, exec, vcc
	ds_write_b64 v248, v[154:155] offset:2048
	s_mov_b64 exec, s[4:5]
	v_bcnt_u32_b32 v119, v246, v119
.Lp2_skip9:
	s_waitcnt lgkmcnt(6)
	v_mfma_f32_32x32x16_bf16 v[198:213], v[38:41], v[172:175], v[198:213]
	v_cmp_le_f32_e64 s[52:53], v197, v184
	v_cmp_le_f32_e32 vcc, v157, v184
	s_andn2_b64 vcc, vcc, s[52:53]
	v_writelane_b32 v33, s52, 2
	v_writelane_b32 v33, s53, 6
	s_cbranch_vccz .Lp2_skip10
	v_mov_b32_e32 v246, vcc_hi
	v_mov_b32_e32 v247, vcc_lo
	v_cndmask_b32_e64 v246, v246, v247, s[48:49]
	s_and_saveexec_b64 s[4:5], vcc
	v_and_b32_e32 v247, v246, v127
	v_bcnt_u32_b32 v247, v247, v118
	v_cmp_gt_u32_e32 vcc, s35, v247
	v_ashrrev_i32_e32 v248, 31, v184
	v_add_u32_e32 v154, s0, v90
	v_bitop3_b32 v155, v184, v248, s97 bitop3:0x1e
	v_lshl_add_u32 v248, v247, 3, v161
	s_and_b64 exec, exec, vcc
	ds_write_b64 v248, v[154:155] offset:2048
	s_mov_b64 exec, s[4:5]
	v_bcnt_u32_b32 v118, v246, v118
.Lp2_skip10:
	s_waitcnt lgkmcnt(5)
	v_mfma_f32_32x32x16_bf16 v[214:229], v[38:41], v[176:179], v[214:229]
	v_max_i32_e32 v246, 0, v8
	v_max_i32_e32 v247, 0, v0
	v_max_i32_e32 v248, 0, v9
	v_max_i32_e32 v249, 0, v1
	v_fma_f32 v184, v100, v246, 0
	v_fma_f32 v185, v101, v247, 0
	s_waitcnt lgkmcnt(4)
	v_mfma_f32_32x32x16_bf16 v[198:213], v[42:45], v[230:233], v[198:213]
	v_fmac_f32_e32 v184, v102, v248
	v_fmac_f32_e32 v185, v103, v249
	v_max_i32_e32 v246, 0, v10
	v_max_i32_e32 v247, 0, v2
	v_max_i32_e32 v248, 0, v11
	v_max_i32_e32 v249, 0, v3
	v_fmac_f32_e32 v184, v104, v246
	v_fmac_f32_e32 v185, v105, v247
	s_waitcnt lgkmcnt(3)
	v_mfma_f32_32x32x16_bf16 v[214:229], v[42:45], v[234:237], v[214:229]
	v_fmac_f32_e32 v184, v106, v248
	v_fmac_f32_e32 v185, v107, v249
	v_max_i32_e32 v246, 0, v12
	v_max_i32_e32 v247, 0, v4
	v_max_i32_e32 v248, 0, v13
	v_max_i32_e32 v249, 0, v5
	v_fmac_f32_e32 v184, v108, v246
	v_fmac_f32_e32 v185, v109, v247
	s_waitcnt lgkmcnt(2)
	v_mfma_f32_32x32x16_bf16 v[198:213], v[46:49], v[238:241], v[198:213]
	v_fmac_f32_e32 v184, v110, v248
	v_fmac_f32_e32 v185, v111, v249
	v_max_i32_e32 v246, 0, v14
	v_max_i32_e32 v247, 0, v6
	v_max_i32_e32 v248, 0, v15
	v_max_i32_e32 v249, 0, v7
	v_fmac_f32_e32 v184, v112, v246
	v_fmac_f32_e32 v185, v113, v247
	s_waitcnt lgkmcnt(1)
	v_mfma_f32_32x32x16_bf16 v[214:229], v[46:49], v[242:245], v[214:229]
	v_fmac_f32_e32 v184, v114, v248
	v_fmac_f32_e32 v185, v115, v249
	v_cmp_le_f32_e64 s[52:53], v250, v185
	v_cmp_le_f32_e32 vcc, v156, v185
	s_andn2_b64 vcc, vcc, s[52:53]
	v_writelane_b32 v33, s52, 1
	v_writelane_b32 v33, s53, 5
	s_cbranch_vccz .Lp2_skip11
	v_mov_b32_e32 v246, vcc_hi
	v_mov_b32_e32 v247, vcc_lo
	v_cndmask_b32_e64 v246, v246, v247, s[48:49]
	s_and_saveexec_b64 s[4:5], vcc
	v_and_b32_e32 v247, v246, v127
	v_bcnt_u32_b32 v247, v247, v119
	v_cmp_gt_u32_e32 vcc, s35, v247
	v_ashrrev_i32_e32 v248, 31, v185
	v_add_u32_e32 v154, s0, v88
	v_bitop3_b32 v155, v185, v248, s97 bitop3:0x1e
	v_lshl_add_u32 v248, v247, 3, v160
	s_and_b64 exec, exec, vcc
	ds_write_b64 v248, v[154:155] offset:2048
	s_mov_b64 exec, s[4:5]
	v_bcnt_u32_b32 v119, v246, v119

.Lp2_c0:
	ds_read_b128 v[164:167], v99 offset:0
	ds_read_b128 v[168:171], v99 offset:4096
	ds_read_b128 v[172:175], v99 offset:1024
	ds_read_b128 v[176:179], v99 offset:5120
	ds_read_b128 v[230:233], v99 offset:2048
	ds_read_b128 v[234:237], v99 offset:6144
	ds_read_b128 v[238:241], v99 offset:3072
	ds_read_b128 v[242:245], v99 offset:7168
	v_max_i32_e32 v246, 0, v206
	v_max_i32_e32 v247, 0, v198
	v_max_i32_e32 v248, 0, v207
	v_max_i32_e32 v249, 0, v199
	v_fma_f32 v184, v100, v246, 0
	v_fma_f32 v185, v101, v247, 0
	v_fmac_f32_e32 v184, v102, v248
	v_fmac_f32_e32 v185, v103, v249
	v_max_i32_e32 v246, 0, v208
	v_max_i32_e32 v247, 0, v200
	v_max_i32_e32 v248, 0, v209
	v_max_i32_e32 v249, 0, v201
	v_fmac_f32_e32 v184, v104, v246
	v_fmac_f32_e32 v185, v105, v247
	v_fmac_f32_e32 v184, v106, v248
	v_fmac_f32_e32 v185, v107, v249
	v_max_i32_e32 v246, 0, v210
	v_max_i32_e32 v247, 0, v202
	v_max_i32_e32 v248, 0, v211
	v_max_i32_e32 v249, 0, v203
	s_waitcnt lgkmcnt(7)
	v_mfma_f32_32x32x16_bf16 v[16:31], v[34:37], v[164:167], 0
	v_fmac_f32_e32 v184, v108, v246
	v_fmac_f32_e32 v185, v109, v247
	v_fmac_f32_e32 v184, v110, v248
	v_fmac_f32_e32 v185, v111, v249
	v_max_i32_e32 v246, 0, v212
	v_max_i32_e32 v247, 0, v204
	v_max_i32_e32 v248, 0, v213
	v_max_i32_e32 v249, 0, v205
	s_waitcnt lgkmcnt(6)
	v_mfma_f32_32x32x16_bf16 v[0:15], v[34:37], v[168:171], 0
	s_waitcnt vmcnt(3)
	ds_write_b128 v140, v[50:53] offset:8192
	s_add_i32 s4, s18, 5
	s_min_i32 s4, s4, s14
	v_mad_i64_i32 v[164:165], s[4:5], s4, v193, v[116:117]
	global_load_dwordx4 v[50:53], v[164:165], off
	v_fmac_f32_e32 v184, v112, v246
	v_fmac_f32_e32 v185, v113, v247
	v_fmac_f32_e32 v184, v114, v248
	v_fmac_f32_e32 v185, v115, v249
	v_cmp_le_f32_e64 s[52:53], v250, v185
	v_cmp_le_f32_e32 vcc, v156, v185
	s_andn2_b64 vcc, vcc, s[52:53]
	v_writelane_b32 v33, s52, 0
	v_writelane_b32 v33, s53, 4
	s_cbranch_vccz .Lp2_skip13
	v_mov_b32_e32 v246, vcc_hi
	v_mov_b32_e32 v247, vcc_lo
	v_cndmask_b32_e64 v246, v246, v247, s[48:49]
	s_and_saveexec_b64 s[4:5], vcc
	v_and_b32_e32 v247, v246, v127
	v_bcnt_u32_b32 v247, v247, v119
	v_cmp_gt_u32_e32 vcc, s35, v247
	v_ashrrev_i32_e32 v248, 31, v185
	v_add_u32_e32 v154, s0, v86
	v_bitop3_b32 v155, v185, v248, s97 bitop3:0x1e
	v_lshl_add_u32 v248, v247, 3, v160
	s_and_b64 exec, exec, vcc
	ds_write_b64 v248, v[154:155] offset:2048
	s_mov_b64 exec, s[4:5]
	v_bcnt_u32_b32 v119, v246, v119
.Lp2_skip13:
	s_waitcnt lgkmcnt(6)
	v_mfma_f32_32x32x16_bf16 v[16:31], v[38:41], v[172:175], v[16:31]
	v_cmp_le_f32_e64 s[52:53], v197, v184
	v_cmp_le_f32_e32 vcc, v157, v184
	s_andn2_b64 vcc, vcc, s[52:53]
	v_writelane_b32 v33, s52, 2
	v_writelane_b32 v33, s53, 6
	s_cbranch_vccz .Lp2_skip14
	v_mov_b32_e32 v246, vcc_hi
	v_mov_b32_e32 v247, vcc_lo
	v_cndmask_b32_e64 v246, v246, v247, s[48:49]
	s_and_saveexec_b64 s[4:5], vcc
	v_and_b32_e32 v247, v246, v127
	v_bcnt_u32_b32 v247, v247, v118
	v_cmp_gt_u32_e32 vcc, s35, v247
	v_ashrrev_i32_e32 v248, 31, v184
	v_add_u32_e32 v154, s0, v86
	v_bitop3_b32 v155, v184, v248, s97 bitop3:0x1e
	v_lshl_add_u32 v248, v247, 3, v161
	s_and_b64 exec, exec, vcc
	ds_write_b64 v248, v[154:155] offset:2048
	s_mov_b64 exec, s[4:5]
	v_bcnt_u32_b32 v118, v246, v118
.Lp2_skip14:
	s_waitcnt lgkmcnt(5)
	v_mfma_f32_32x32x16_bf16 v[0:15], v[38:41], v[176:179], v[0:15]
	v_max_i32_e32 v246, 0, v222
	v_max_i32_e32 v247, 0, v214
	v_max_i32_e32 v248, 0, v223
	v_max_i32_e32 v249, 0, v215
	v_fma_f32 v184, v100, v246, 0
	v_fma_f32 v185, v101, v247, 0
	s_waitcnt lgkmcnt(4)
	v_mfma_f32_32x32x16_bf16 v[16:31], v[42:45], v[230:233], v[16:31]
	v_fmac_f32_e32 v184, v102, v248
	v_fmac_f32_e32 v185, v103, v249
	v_max_i32_e32 v246, 0, v224
	v_max_i32_e32 v247, 0, v216
	v_max_i32_e32 v248, 0, v225
	v_max_i32_e32 v249, 0, v217
	v_fmac_f32_e32 v184, v104, v246
	v_fmac_f32_e32 v185, v105, v247
	s_waitcnt lgkmcnt(3)
	v_mfma_f32_32x32x16_bf16 v[0:15], v[42:45], v[234:237], v[0:15]
	v_fmac_f32_e32 v184, v106, v248
	v_fmac_f32_e32 v185, v107, v249
	v_max_i32_e32 v246, 0, v226
	v_max_i32_e32 v247, 0, v218
	v_max_i32_e32 v248, 0, v227
	v_max_i32_e32 v249, 0, v219
	v_fmac_f32_e32 v184, v108, v246
	v_fmac_f32_e32 v185, v109, v247
	s_waitcnt lgkmcnt(2)
	v_mfma_f32_32x32x16_bf16 v[16:31], v[46:49], v[238:241], v[16:31]
	v_fmac_f32_e32 v184, v110, v248
	v_fmac_f32_e32 v185, v111, v249
	v_max_i32_e32 v246, 0, v228
	v_max_i32_e32 v247, 0, v220
	v_max_i32_e32 v248, 0, v229
	v_max_i32_e32 v249, 0, v221
	v_fmac_f32_e32 v184, v112, v246
	v_fmac_f32_e32 v185, v113, v247
	s_waitcnt lgkmcnt(1)
	v_mfma_f32_32x32x16_bf16 v[0:15], v[46:49], v[242:245], v[0:15]
	v_fmac_f32_e32 v184, v114, v248
	v_fmac_f32_e32 v185, v115, v249
	v_cmp_le_f32_e64 s[52:53], v250, v185
	v_cmp_le_f32_e32 vcc, v156, v185
	s_andn2_b64 vcc, vcc, s[52:53]
	v_writelane_b32 v33, s52, 1
	v_writelane_b32 v33, s53, 5
	s_cbranch_vccz .Lp2_skip15
	v_mov_b32_e32 v246, vcc_hi
	v_mov_b32_e32 v247, vcc_lo
	v_cndmask_b32_e64 v246, v246, v247, s[48:49]
	s_and_saveexec_b64 s[4:5], vcc
	v_and_b32_e32 v247, v246, v127
	v_bcnt_u32_b32 v247, v247, v119
	v_cmp_gt_u32_e32 vcc, s35, v247
	v_ashrrev_i32_e32 v248, 31, v185
	v_add_u32_e32 v154, s0, v84
	v_bitop3_b32 v155, v185, v248, s97 bitop3:0x1e
	v_lshl_add_u32 v248, v247, 3, v160
	s_and_b64 exec, exec, vcc
	ds_write_b64 v248, v[154:155] offset:2048
	s_mov_b64 exec, s[4:5]
	v_bcnt_u32_b32 v119, v246, v119
